# w_out GEMM epilogue: per row pair the wait for the 8 residual loads hoisted in front of the exec-masked block, the two following vmcnt(0) (store acknowledgements in the common path) removed
# speedup vs baseline: 1.0024x; 1.0024x over previous
; __device__ __forceinline__ float xor32f(float v) { const auto rr = __builtin_amdgcn_permlane32_swap(__float_as_uint(v), __float_as_uint(v), false, false); const unsigned me = __float_as_uint(v); return __uint_as_float(rr[0] == me ? rr[1] : rr[0]); }
; __device__ __forceinline__ float xor16f(float v) { return __uint_as_float((unsigned)__builtin_amdgcn_ds_swizzle((int)__float_as_uint(v), 0x401F)); }
; __device__ __forceinline__ u32x4 pack8(const f32x4& a, const f32x4& b) { u32x4 w; w.x = cvt_pk_bf16(a[0], a[1]); w.y = cvt_pk_bf16(a[2], a[3]); w.z = cvt_pk_bf16(b[0], b[1]); w.w = cvt_pk_bf16(b[2], b[3]); return w; }
;     __device__ __forceinline__ void apply(const Ld& d, int row, int c0, int, int, int, const f32x4& a0, const f32x4& b0, const f32x4& a1, const f32x4& b1) const { half(d.g0, row, c0, a0, b0); half(d.g1, row, c0 + 128, a1, b1); }
;     __device__ __forceinline__ void apply(const Ld& d, int row, int c0, int, int, int, const f32x4& a0, const f32x4& b0, const f32x4& a1, const f32x4& b1) const { half(d.g0, d.p0, row, c0, a0, b0); half(d.g1, d.p1, row, c0 + 128, a1, b1); }
;     __device__ __forceinline__ void apply(const Ld& d, int row, int c0, int pn, int wc, int fq, const f32x4& a0, const f32x4& b0, const f32x4& a1, const f32x4& b1) const {
;         float* r = hres_row(out, metah, row);
;         f32x4 v0 = (f32x4){0.f, 0.f, 0.f, 0.f}, v1 = v0, v2 = v0, v3 = v0;
;         if (r) { v0 = d.v[0] + a0; v1 = d.v[1] + b0; v2 = d.v[2] + a1; v3 = d.v[3] + b1;
;             *(f32x4*)(r + c0) = v0; *(f32x4*)(r + c0 + 4) = v1; *(f32x4*)(r + c0 + 128) = v2; *(f32x4*)(r + c0 + 132) = v3; }
;         if (!hb) return;
;         *(u32x4*)(hb + (size_t)row * DM + c0) = pack8(v0, v1); *(u32x4*)(hb + (size_t)row * DM + c0 + 128) = pack8(v2, v3);
;         const f32x4 sq = v0 * v0 + v1 * v1 + v2 * v2 + v3 * v3;
;         float ss = (sq[0] + sq[1]) + (sq[2] + sq[3]);
;         ss += xor16f(ss); ss += xor32f(ss);
;         if (fq == 0) ssqh[(size_t)row * 16 + 4 * pn + wc] = ss;
.LBB0_469:
	s_or_b64 exec, exec, s[0:1]
	v_cmp_ne_u64_e32 vcc, 0, v[208:209]
	v_mov_b32_e32 v166, 0
	v_mov_b32_e32 v167, 0
	v_mov_b32_e32 v168, 0
	v_mov_b32_e32 v169, 0
	v_mov_b32_e32 v170, 0
	v_mov_b32_e32 v171, 0
	v_mov_b32_e32 v172, 0
	v_mov_b32_e32 v173, 0
	v_mov_b32_e32 v174, 0
	v_mov_b32_e32 v175, 0
	v_mov_b32_e32 v176, 0
	v_mov_b32_e32 v177, 0
	v_mov_b32_e32 v178, 0
	v_mov_b32_e32 v179, 0
	v_mov_b32_e32 v180, 0
	v_mov_b32_e32 v181, 0
	s_waitcnt vmcnt(0)
	s_and_saveexec_b64 s[0:1], vcc
	s_cbranch_execz .LBB0_471
	v_pk_add_f32 v[180:181], v[132:133], v[160:161]
	v_pk_add_f32 v[178:179], v[130:131], v[158:159]
	v_pk_add_f32 v[176:177], v[128:129], v[152:153]
	v_pk_add_f32 v[174:175], v[126:127], v[150:151]
	v_pk_add_f32 v[172:173], v[124:125], v[164:165]
	v_pk_add_f32 v[170:171], v[122:123], v[162:163]
	v_pk_add_f32 v[168:169], v[120:121], v[156:157]
	v_pk_add_f32 v[166:167], v[118:119], v[154:155]
	v_lshl_add_u64 v[150:151], v[204:205], 2, v[208:209]
	global_store_dwordx4 v[150:151], v[178:181], off
	global_store_dwordx4 v[150:151], v[174:177], off offset:16
	global_store_dwordx4 v[150:151], v[170:173], off offset:512
	global_store_dwordx4 v[150:151], v[166:169], off offset:528
.LBB0_471:
	s_or_b64 exec, exec, s[0:1]
	v_readlane_b32 s0, v254, 54
	v_readlane_b32 s1, v254, 55
	s_andn2_b64 vcc, exec, s[0:1]
	s_nop 0
	v_cndmask_b32_e64 v0, 0, 1, s[0:1]
	v_cmp_ne_u32_e64 s[86:87], 1, v0
	s_cbranch_vccnz .LBB0_475
	v_ashrrev_i32_e32 v207, 31, v206
	v_lshlrev_b64 v[154:155], 11, v[206:207]
	v_lshl_add_u64 v[154:155], s[60:61], 0, v[154:155]
	v_cvt_pk_bf16_f32 v150, v178, v179
	v_cvt_pk_bf16_f32 v151, v180, v181
	v_cvt_pk_bf16_f32 v152, v174, v175
	v_cvt_pk_bf16_f32 v153, v176, v177
	v_lshl_add_u64 v[154:155], v[204:205], 1, v[154:155]
	global_store_dwordx4 v[154:155], v[150:153], off
	s_nop 1
	v_cvt_pk_bf16_f32 v150, v170, v171
	v_cvt_pk_bf16_f32 v151, v172, v173
	v_cvt_pk_bf16_f32 v152, v166, v167
	v_cvt_pk_bf16_f32 v153, v168, v169
	global_store_dwordx4 v[154:155], v[150:153], off offset:256
	s_nop 1
	v_pk_mul_f32 v[150:151], v[178:179], v[178:179]
	v_pk_mul_f32 v[152:153], v[180:181], v[180:181]
	v_pk_fma_f32 v[150:151], v[174:175], v[174:175], v[150:151]
	v_pk_fma_f32 v[152:153], v[176:177], v[176:177], v[152:153]
	v_pk_fma_f32 v[150:151], v[170:171], v[170:171], v[150:151]
	v_pk_fma_f32 v[152:153], v[172:173], v[172:173], v[152:153]
	v_pk_fma_f32 v[150:151], v[166:167], v[166:167], v[150:151]
	v_pk_fma_f32 v[152:153], v[168:169], v[168:169], v[152:153]
	v_add_f32_e32 v0, v150, v151
	v_add_f32_e32 v150, v152, v153
	v_add_f32_e32 v0, v0, v150
	ds_swizzle_b32 v150, v0 offset:swizzle(SWAP,16)
	s_waitcnt lgkmcnt(0)
	v_add_f32_e32 v0, v0, v150
	v_mov_b32_e32 v150, v0
	v_mov_b32_e32 v151, v0
	s_nop 1
	v_permlane32_swap_b32_e32 v150, v151
	s_and_saveexec_b64 s[0:1], s[82:83]
	s_cbranch_execz .LBB0_474
	v_cmp_eq_u32_e32 vcc, v150, v0
	s_lshl_b32 s22, s71, 2
	s_ashr_i32 s23, s22, 31
	v_cndmask_b32_e32 v150, v150, v151, vcc
	v_add_f32_e32 v0, v0, v150
	v_lshlrev_b64 v[150:151], 6, v[206:207]
	v_lshl_add_u64 v[150:151], s[24:25], 0, v[150:151]
	v_lshl_add_u64 v[150:151], s[22:23], 2, v[150:151]
	s_lshl_b32 s90, s80, 2
	v_lshl_add_u64 v[150:151], v[150:151], 0, s[90:91]
	global_store_dword v[150:151], v0, off

; __device__ __forceinline__ float* hres_row(float* out, float* metah, int row) {
;     const int b = row / LP, t = row - b * LP - PADF;
;     if (t < 0) return nullptr;
;     if (t < NMETA) return metah + (size_t)(b * NMETA + t) * DM;
;     return out + ((size_t)b * SEQ + (t - NMETA)) * DM;
; }
.LBB0_475:
	v_add_u32_e32 v166, s64, v235
	v_mul_hi_i32 v0, v166, s97
	v_lshrrev_b32_e32 v150, 31, v0
	v_ashrrev_i32_e32 v0, 12, v0
	v_add_u32_e32 v150, v0, v150
	v_mad_i32_i24 v0, v150, s26, v166
	v_cmp_lt_i32_e32 vcc, s27, v0
	v_mov_b64_e32 v[168:169], 0
	s_and_saveexec_b64 s[0:1], vcc
	s_cbranch_execz .LBB0_481
	s_movk_i32 s22, 0x7f
	v_cmp_lt_u32_e32 vcc, s22, v0
	s_and_saveexec_b64 s[22:23], vcc
	s_xor_b64 s[22:23], exec, s[22:23]
	s_cbranch_execz .LBB0_478
	v_ashrrev_i32_e32 v151, 31, v150
	v_readlane_b32 s36, v253, 31
	v_add_u32_e32 v0, 0xffffff80, v0
	v_lshlrev_b64 v[150:151], 25, v[150:151]
	v_readlane_b32 s37, v253, 32
	v_lshlrev_b64 v[152:153], 12, v[0:1]
	s_nop 0
	v_lshl_add_u64 v[150:151], s[36:37], 0, v[150:151]
	v_lshl_add_u64 v[168:169], v[150:151], 0, v[152:153]

; __device__ __forceinline__ float xor32f(float v) { const auto rr = __builtin_amdgcn_permlane32_swap(__float_as_uint(v), __float_as_uint(v), false, false); const unsigned me = __float_as_uint(v); return __uint_as_float(rr[0] == me ? rr[1] : rr[0]); }
; __device__ __forceinline__ float xor16f(float v) { return __uint_as_float((unsigned)__builtin_amdgcn_ds_swizzle((int)__float_as_uint(v), 0x401F)); }
; __device__ __forceinline__ u32x4 pack8(const f32x4& a, const f32x4& b) { u32x4 w; w.x = cvt_pk_bf16(a[0], a[1]); w.y = cvt_pk_bf16(a[2], a[3]); w.z = cvt_pk_bf16(b[0], b[1]); w.w = cvt_pk_bf16(b[2], b[3]); return w; }
;     __device__ __forceinline__ void apply(const Ld& d, int row, int c0, int, int, int, const f32x4& a0, const f32x4& b0, const f32x4& a1, const f32x4& b1) const { half(d.g0, row, c0, a0, b0); half(d.g1, row, c0 + 128, a1, b1); }
;     __device__ __forceinline__ void apply(const Ld& d, int row, int c0, int, int, int, const f32x4& a0, const f32x4& b0, const f32x4& a1, const f32x4& b1) const { half(d.g0, d.p0, row, c0, a0, b0); half(d.g1, d.p1, row, c0 + 128, a1, b1); }
;     __device__ __forceinline__ void apply(const Ld& d, int row, int c0, int pn, int wc, int fq, const f32x4& a0, const f32x4& b0, const f32x4& a1, const f32x4& b1) const {
;         float* r = hres_row(out, metah, row);
;         f32x4 v0 = (f32x4){0.f, 0.f, 0.f, 0.f}, v1 = v0, v2 = v0, v3 = v0;
;         if (r) { v0 = d.v[0] + a0; v1 = d.v[1] + b0; v2 = d.v[2] + a1; v3 = d.v[3] + b1;
;             *(f32x4*)(r + c0) = v0; *(f32x4*)(r + c0 + 4) = v1; *(f32x4*)(r + c0 + 128) = v2; *(f32x4*)(r + c0 + 132) = v3; }
;         if (!hb) return;
;         *(u32x4*)(hb + (size_t)row * DM + c0) = pack8(v0, v1); *(u32x4*)(hb + (size_t)row * DM + c0 + 128) = pack8(v2, v3);
;         const f32x4 sq = v0 * v0 + v1 * v1 + v2 * v2 + v3 * v3;
;         float ss = (sq[0] + sq[1]) + (sq[2] + sq[3]);
;         ss += xor16f(ss); ss += xor32f(ss);
;         if (fq == 0) ssqh[(size_t)row * 16 + 4 * pn + wc] = ss;
.LBB0_517:
	s_or_b64 exec, exec, s[0:1]
	v_cmp_ne_u64_e32 vcc, 0, v[210:211]
	v_mov_b32_e32 v166, 0
	v_mov_b32_e32 v167, 0
	v_mov_b32_e32 v168, 0
	v_mov_b32_e32 v169, 0
	v_mov_b32_e32 v170, 0
	v_mov_b32_e32 v171, 0
	v_mov_b32_e32 v172, 0
	v_mov_b32_e32 v173, 0
	v_mov_b32_e32 v174, 0
	v_mov_b32_e32 v175, 0
	v_mov_b32_e32 v176, 0
	v_mov_b32_e32 v177, 0
	v_mov_b32_e32 v178, 0
	v_mov_b32_e32 v179, 0
	v_mov_b32_e32 v180, 0
	v_mov_b32_e32 v181, 0
	s_waitcnt vmcnt(0)
	s_and_saveexec_b64 s[0:1], vcc
	s_cbranch_execz .LBB0_519
	v_pk_add_f32 v[180:181], v[100:101], v[160:161]
	v_pk_add_f32 v[178:179], v[98:99], v[158:159]
	v_pk_add_f32 v[176:177], v[96:97], v[152:153]
	v_pk_add_f32 v[174:175], v[94:95], v[150:151]
	v_pk_add_f32 v[172:173], v[92:93], v[164:165]
	v_pk_add_f32 v[170:171], v[90:91], v[162:163]
	v_pk_add_f32 v[168:169], v[88:89], v[156:157]
	v_pk_add_f32 v[166:167], v[86:87], v[154:155]
	v_lshl_add_u64 v[150:151], v[204:205], 2, v[210:211]
	global_store_dwordx4 v[150:151], v[178:181], off
	global_store_dwordx4 v[150:151], v[174:177], off offset:16
	global_store_dwordx4 v[150:151], v[170:173], off offset:512
	global_store_dwordx4 v[150:151], v[166:169], off offset:528
.LBB0_519:
	s_or_b64 exec, exec, s[0:1]
	s_and_b64 vcc, exec, s[86:87]
	s_cbranch_vccnz .LBB0_523
	v_ashrrev_i32_e32 v209, 31, v208
	v_lshlrev_b64 v[154:155], 11, v[208:209]
	v_lshl_add_u64 v[154:155], s[60:61], 0, v[154:155]
	v_cvt_pk_bf16_f32 v150, v178, v179
	v_cvt_pk_bf16_f32 v151, v180, v181
	v_cvt_pk_bf16_f32 v152, v174, v175
	v_cvt_pk_bf16_f32 v153, v176, v177
	v_lshl_add_u64 v[154:155], v[204:205], 1, v[154:155]
	global_store_dwordx4 v[154:155], v[150:153], off
	s_nop 1
	v_cvt_pk_bf16_f32 v150, v170, v171
	v_cvt_pk_bf16_f32 v151, v172, v173
	v_cvt_pk_bf16_f32 v152, v166, v167
	v_cvt_pk_bf16_f32 v153, v168, v169
	global_store_dwordx4 v[154:155], v[150:153], off offset:256
	s_nop 1
	v_pk_mul_f32 v[150:151], v[178:179], v[178:179]
	v_pk_mul_f32 v[152:153], v[180:181], v[180:181]
	v_pk_fma_f32 v[150:151], v[174:175], v[174:175], v[150:151]
	v_pk_fma_f32 v[152:153], v[176:177], v[176:177], v[152:153]
	v_pk_fma_f32 v[150:151], v[170:171], v[170:171], v[150:151]
	v_pk_fma_f32 v[152:153], v[172:173], v[172:173], v[152:153]
	v_pk_fma_f32 v[150:151], v[166:167], v[166:167], v[150:151]
	v_pk_fma_f32 v[152:153], v[168:169], v[168:169], v[152:153]
	v_add_f32_e32 v0, v150, v151
	v_add_f32_e32 v150, v152, v153
	v_add_f32_e32 v0, v0, v150
	ds_swizzle_b32 v150, v0 offset:swizzle(SWAP,16)
	s_waitcnt lgkmcnt(0)
	v_add_f32_e32 v0, v0, v150
	v_mov_b32_e32 v150, v0
	v_mov_b32_e32 v151, v0
	s_nop 1
	v_permlane32_swap_b32_e32 v150, v151
	s_and_saveexec_b64 s[0:1], s[82:83]
	s_cbranch_execz .LBB0_522
	v_cmp_eq_u32_e32 vcc, v150, v0
	s_lshl_b32 s22, s71, 2
	s_ashr_i32 s23, s22, 31
	v_cndmask_b32_e32 v150, v150, v151, vcc
	v_add_f32_e32 v0, v0, v150
	v_lshlrev_b64 v[150:151], 6, v[208:209]
	v_lshl_add_u64 v[150:151], s[24:25], 0, v[150:151]
	v_lshl_add_u64 v[150:151], s[22:23], 2, v[150:151]
	s_lshl_b32 s90, s80, 2
	v_lshl_add_u64 v[150:151], v[150:151], 0, s[90:91]
	global_store_dword v[150:151], v0, off

; __device__ __forceinline__ float* hres_row(float* out, float* metah, int row) {
;     const int b = row / LP, t = row - b * LP - PADF;
;     if (t < 0) return nullptr;
;     if (t < NMETA) return metah + (size_t)(b * NMETA + t) * DM;
;     return out + ((size_t)b * SEQ + (t - NMETA)) * DM;
; }
.LBB0_523:
	v_add_u32_e32 v166, s64, v237
	v_mul_hi_i32 v0, v166, s97
	v_lshrrev_b32_e32 v150, 31, v0
	v_ashrrev_i32_e32 v0, 12, v0
	v_add_u32_e32 v150, v0, v150
	v_mad_i32_i24 v0, v150, s26, v166
	v_cmp_lt_i32_e32 vcc, s27, v0
	v_mov_b64_e32 v[168:169], 0
	s_and_saveexec_b64 s[0:1], vcc
	s_cbranch_execz .LBB0_529
	s_movk_i32 s22, 0x7f
	v_cmp_lt_u32_e32 vcc, s22, v0
	s_and_saveexec_b64 s[22:23], vcc
	s_xor_b64 s[22:23], exec, s[22:23]
	s_cbranch_execz .LBB0_526
	v_ashrrev_i32_e32 v151, 31, v150
	v_readlane_b32 s36, v253, 31
	v_add_u32_e32 v0, 0xffffff80, v0
	v_lshlrev_b64 v[150:151], 25, v[150:151]
	v_readlane_b32 s37, v253, 32
	v_lshlrev_b64 v[152:153], 12, v[0:1]
	s_nop 0
	v_lshl_add_u64 v[150:151], s[36:37], 0, v[150:151]
	v_lshl_add_u64 v[168:169], v[150:151], 0, v[152:153]

;     __device__ __forceinline__ void apply(const Ld& d, int row, int c0, int, int, int, const f32x4& a0, const f32x4& b0, const f32x4& a1, const f32x4& b1) const { half(d.g0, row, c0, a0, b0); half(d.g1, row, c0 + 128, a1, b1); }
;     __device__ __forceinline__ void apply(const Ld& d, int row, int c0, int, int, int, const f32x4& a0, const f32x4& b0, const f32x4& a1, const f32x4& b1) const { half(d.g0, d.p0, row, c0, a0, b0); half(d.g1, d.p1, row, c0 + 128, a1, b1); }
;     __device__ __forceinline__ void apply(const Ld& d, int row, int c0, int pn, int wc, int fq, const f32x4& a0, const f32x4& b0, const f32x4& a1, const f32x4& b1) const {
;         float* r = hres_row(out, metah, row);
;         f32x4 v0 = (f32x4){0.f, 0.f, 0.f, 0.f}, v1 = v0, v2 = v0, v3 = v0;
;         if (r) { v0 = d.v[0] + a0; v1 = d.v[1] + b0; v2 = d.v[2] + a1; v3 = d.v[3] + b1;
;             *(f32x4*)(r + c0) = v0; *(f32x4*)(r + c0 + 4) = v1; *(f32x4*)(r + c0 + 128) = v2; *(f32x4*)(r + c0 + 132) = v3; }
.LBB0_565:
	s_or_b64 exec, exec, s[0:1]
	v_cmp_ne_u64_e32 vcc, 0, v[210:211]
	v_mov_b32_e32 v166, 0
	v_mov_b32_e32 v167, 0
	v_mov_b32_e32 v168, 0
	v_mov_b32_e32 v169, 0
	v_mov_b32_e32 v170, 0
	v_mov_b32_e32 v171, 0
	v_mov_b32_e32 v172, 0
	v_mov_b32_e32 v173, 0
	v_mov_b32_e32 v174, 0
	v_mov_b32_e32 v175, 0
	v_mov_b32_e32 v176, 0
	v_mov_b32_e32 v177, 0
	v_mov_b32_e32 v178, 0
	v_mov_b32_e32 v179, 0
	v_mov_b32_e32 v180, 0
	v_mov_b32_e32 v181, 0
	s_waitcnt vmcnt(0)
	s_and_saveexec_b64 s[0:1], vcc
	s_cbranch_execz .LBB0_567
	v_pk_add_f32 v[180:181], v[68:69], v[160:161]
	v_pk_add_f32 v[178:179], v[66:67], v[158:159]
	v_pk_add_f32 v[176:177], v[64:65], v[152:153]
	v_pk_add_f32 v[174:175], v[62:63], v[150:151]
	v_pk_add_f32 v[172:173], v[60:61], v[164:165]
	v_pk_add_f32 v[170:171], v[58:59], v[162:163]
	v_pk_add_f32 v[168:169], v[56:57], v[156:157]
	v_pk_add_f32 v[166:167], v[54:55], v[154:155]
	v_lshl_add_u64 v[150:151], v[204:205], 2, v[210:211]
	global_store_dwordx4 v[150:151], v[178:181], off
	global_store_dwordx4 v[150:151], v[174:177], off offset:16
	global_store_dwordx4 v[150:151], v[170:173], off offset:512
	global_store_dwordx4 v[150:151], v[166:169], off offset:528

; __device__ __forceinline__ float* hres_row(float* out, float* metah, int row) {
;     const int b = row / LP, t = row - b * LP - PADF;
;     if (t < 0) return nullptr;
;     if (t < NMETA) return metah + (size_t)(b * NMETA + t) * DM;
;     return out + ((size_t)b * SEQ + (t - NMETA)) * DM;
; }
.LBB0_571:
	v_add_u32_e32 v166, 0x90, v206
	v_mul_hi_i32 v0, v166, s97
	v_lshrrev_b32_e32 v150, 31, v0
	v_ashrrev_i32_e32 v0, 12, v0
	v_add_u32_e32 v150, v0, v150
	v_mad_i32_i24 v0, v150, s26, v166
	v_cmp_lt_i32_e32 vcc, s27, v0
	v_mov_b64_e32 v[168:169], 0
	s_and_saveexec_b64 s[0:1], vcc
	s_cbranch_execz .LBB0_577
	s_movk_i32 s22, 0x7f
	v_cmp_lt_u32_e32 vcc, s22, v0
	s_and_saveexec_b64 s[22:23], vcc
	s_xor_b64 s[22:23], exec, s[22:23]
	s_cbranch_execz .LBB0_574
	v_ashrrev_i32_e32 v151, 31, v150
	v_readlane_b32 s36, v253, 31
	v_add_u32_e32 v0, 0xffffff80, v0
	v_lshlrev_b64 v[150:151], 25, v[150:151]
	v_readlane_b32 s37, v253, 32
	v_lshlrev_b64 v[152:153], 12, v[0:1]
	s_nop 0
	v_lshl_add_u64 v[150:151], s[36:37], 0, v[150:151]
	v_lshl_add_u64 v[168:169], v[150:151], 0, v[152:153]

;     __device__ __forceinline__ void apply(const Ld& d, int row, int c0, int, int, int, const f32x4& a0, const f32x4& b0, const f32x4& a1, const f32x4& b1) const { half(d.g0, row, c0, a0, b0); half(d.g1, row, c0 + 128, a1, b1); }
;     __device__ __forceinline__ void apply(const Ld& d, int row, int c0, int, int, int, const f32x4& a0, const f32x4& b0, const f32x4& a1, const f32x4& b1) const { half(d.g0, d.p0, row, c0, a0, b0); half(d.g1, d.p1, row, c0 + 128, a1, b1); }
;     __device__ __forceinline__ void apply(const Ld& d, int row, int c0, int pn, int wc, int fq, const f32x4& a0, const f32x4& b0, const f32x4& a1, const f32x4& b1) const {
;         float* r = hres_row(out, metah, row);
;         f32x4 v0 = (f32x4){0.f, 0.f, 0.f, 0.f}, v1 = v0, v2 = v0, v3 = v0;
;         if (r) { v0 = d.v[0] + a0; v1 = d.v[1] + b0; v2 = d.v[2] + a1; v3 = d.v[3] + b1;
;             *(f32x4*)(r + c0) = v0; *(f32x4*)(r + c0 + 4) = v1; *(f32x4*)(r + c0 + 128) = v2; *(f32x4*)(r + c0 + 132) = v3; }
.LBB0_613:
	s_or_b64 exec, exec, s[0:1]
	v_cmp_ne_u64_e32 vcc, 0, v[210:211]
	v_mov_b32_e32 v166, 0
	v_mov_b32_e32 v167, 0
	v_mov_b32_e32 v168, 0
	v_mov_b32_e32 v169, 0
	v_mov_b32_e32 v170, 0
	v_mov_b32_e32 v171, 0
	v_mov_b32_e32 v172, 0
	v_mov_b32_e32 v173, 0
	v_mov_b32_e32 v174, 0
	v_mov_b32_e32 v175, 0
	v_mov_b32_e32 v176, 0
	v_mov_b32_e32 v177, 0
	v_mov_b32_e32 v178, 0
	v_mov_b32_e32 v179, 0
	v_mov_b32_e32 v180, 0
	v_mov_b32_e32 v181, 0
	s_waitcnt vmcnt(0)
	s_and_saveexec_b64 s[0:1], vcc
	s_cbranch_execz .LBB0_615
	v_pk_add_f32 v[180:181], v[36:37], v[160:161]
	v_pk_add_f32 v[178:179], v[34:35], v[158:159]
	v_pk_add_f32 v[176:177], v[32:33], v[152:153]
	v_pk_add_f32 v[174:175], v[30:31], v[150:151]
	v_pk_add_f32 v[172:173], v[28:29], v[164:165]
	v_pk_add_f32 v[170:171], v[26:27], v[162:163]
	v_pk_add_f32 v[168:169], v[24:25], v[156:157]
	v_pk_add_f32 v[166:167], v[22:23], v[154:155]
	v_lshl_add_u64 v[150:151], v[204:205], 2, v[210:211]
	global_store_dwordx4 v[150:151], v[178:181], off
	global_store_dwordx4 v[150:151], v[174:177], off offset:16
	global_store_dwordx4 v[150:151], v[170:173], off offset:512
	global_store_dwordx4 v[150:151], v[166:169], off offset:528

; __device__ __forceinline__ float* hres_row(float* out, float* metah, int row) {
;     const int b = row / LP, t = row - b * LP - PADF;
;     if (t < 0) return nullptr;
;     if (t < NMETA) return metah + (size_t)(b * NMETA + t) * DM;
;     return out + ((size_t)b * SEQ + (t - NMETA)) * DM;
; }
.LBB0_619:
	v_add_u32_e32 v166, 0xb0, v206
	v_mul_hi_i32 v0, v166, s97
	v_lshrrev_b32_e32 v150, 31, v0
	v_ashrrev_i32_e32 v0, 12, v0
	v_add_u32_e32 v150, v0, v150
	v_mad_i32_i24 v0, v150, s26, v166
	v_cmp_lt_i32_e32 vcc, s27, v0
	v_mov_b64_e32 v[168:169], 0
	s_and_saveexec_b64 s[0:1], vcc
	s_cbranch_execz .LBB0_625
	s_movk_i32 s22, 0x7f
	v_cmp_lt_u32_e32 vcc, s22, v0
	s_and_saveexec_b64 s[22:23], vcc
	s_xor_b64 s[22:23], exec, s[22:23]
	s_cbranch_execz .LBB0_622
	v_ashrrev_i32_e32 v151, 31, v150
	v_readlane_b32 s36, v253, 31
	v_add_u32_e32 v0, 0xffffff80, v0
	v_lshlrev_b64 v[150:151], 25, v[150:151]
	v_readlane_b32 s37, v253, 32
	v_lshlrev_b64 v[152:153], 12, v[0:1]
	s_nop 0
	v_lshl_add_u64 v[150:151], s[36:37], 0, v[150:151]
	v_lshl_add_u64 v[168:169], v[150:151], 0, v[152:153]
